# attention: row-sum accumulation with 15 v_pk_add_f32 instead of 32 serial v_add_f32 (on top of v7)
# baseline (speedup 1.0000x reference)
.Latt_prio_done:
.LBB0_674:
	s_add_i32 s2, s67, -1
	s_and_b32 s2, s2, 3
	s_mulk_i32 s2, 0x3400
	s_and_b32 s71, s67, 2
	s_add_i32 s2, s2, 0
	s_xor_b32 s3, s71, 2
	v_add_u32_e32 v0, s2, v192
	s_mulk_i32 s3, 0x2400
	s_waitcnt vmcnt(5)
	ds_write_b128 v0, v[152:155]
	v_add_u32_e32 v0, s2, v185
	s_add_i32 s2, s67, 5
	s_waitcnt vmcnt(4)
	ds_write_b128 v0, v[156:159] offset:128
	v_add_u32_e32 v0, s3, v193
	s_min_i32 s46, s2, s66
	s_add_i32 s2, s67, 4
	v_add_u32_e32 v0, 0xd000, v0
	s_min_i32 s2, s2, s66
	s_lshl_b64 s[4:5], s[46:47], 16
	s_mov_b32 s3, s47
	s_waitcnt vmcnt(3)
	ds_write2_b64 v0, v[172:173], v[174:175] offset1:2
	v_lshl_add_u64 v[2:3], v[186:187], 0, s[4:5]
	s_lshl_b64 s[4:5], s[46:47], 12
	s_lshl_b64 s[2:3], s[2:3], 7
	v_lshl_add_u64 v[4:5], v[188:189], 0, s[4:5]
	global_load_dwordx4 v[152:155], v[2:3], off
	global_load_dwordx4 v[156:159], v[4:5], off
	v_lshl_add_u64 v[2:3], v[190:191], 0, s[2:3]
	global_load_dwordx4 v[172:175], v[2:3], off
	s_add_i32 s70, s67, 1
	s_and_b32 s69, s70, 3
	s_cmp_gt_i32 s67, s65
	s_cbranch_scc1 .LBB0_685
	s_mul_i32 s2, s69, 0x3400
	v_add_u32_e32 v0, s2, v196
	ds_read_b128 v[2:5], v0
	ds_read_b128 v[6:9], v0 offset:6656
	s_waitcnt lgkmcnt(1)
	v_mfma_f32_32x32x16_bf16 v[112:127], v[2:5], v[128:131], v[48:63]
	ds_read_b128 v[10:13], v0 offset:32
	ds_read_b128 v[202:205], v0 offset:6688
	v_cvt_pk_bf16_f32 v176, v80, v81
	s_waitcnt lgkmcnt(2)
	v_mfma_f32_32x32x16_bf16 v[96:111], v[6:9], v[128:131], v[48:63]
	v_pk_add_f32 v[210:211], v[80:81], v[82:83]
	v_cvt_pk_bf16_f32 v177, v82, v83
	s_waitcnt lgkmcnt(1)
	v_mfma_f32_32x32x16_bf16 v[112:127], v[10:13], v[132:135], v[112:127]
	ds_read_b128 v[2:5], v0 offset:64
	ds_read_b128 v[6:9], v0 offset:6720
	v_pk_add_f32 v[210:211], v[210:211], v[84:85]
	v_pk_add_f32 v[210:211], v[210:211], v[86:87]
	v_cvt_pk_bf16_f32 v178, v84, v85
	v_cvt_pk_bf16_f32 v179, v86, v87
	s_waitcnt lgkmcnt(2)
	v_mfma_f32_32x32x16_bf16 v[96:111], v[202:205], v[132:135], v[96:111]
	v_pk_add_f32 v[210:211], v[210:211], v[88:89]
	v_cvt_pk_bf16_f32 v10, v88, v89
	s_waitcnt lgkmcnt(1)
	v_mfma_f32_32x32x16_bf16 v[112:127], v[2:5], v[136:139], v[112:127]
	ds_read_b128 v[80:83], v0 offset:96
	ds_read_b128 v[202:205], v0 offset:6752
	v_pk_add_f32 v[210:211], v[210:211], v[90:91]
	v_cvt_pk_bf16_f32 v11, v90, v91
	s_waitcnt lgkmcnt(2)
	v_mfma_f32_32x32x16_bf16 v[96:111], v[6:9], v[136:139], v[96:111]
	v_pk_add_f32 v[210:211], v[210:211], v[92:93]
	v_pk_add_f32 v[210:211], v[210:211], v[94:95]
	v_cvt_pk_bf16_f32 v12, v92, v93
	v_cvt_pk_bf16_f32 v13, v94, v95
	s_waitcnt lgkmcnt(1)
	v_mfma_f32_32x32x16_bf16 v[112:127], v[80:83], v[140:143], v[112:127]
	ds_read_b128 v[2:5], v0 offset:128
	ds_read_b128 v[206:209], v0 offset:6784
	v_pk_add_f32 v[210:211], v[210:211], v[16:17]
	v_cvt_pk_bf16_f32 v6, v16, v17
	s_waitcnt lgkmcnt(2)
	v_mfma_f32_32x32x16_bf16 v[96:111], v[202:205], v[140:143], v[96:111]
	v_pk_add_f32 v[210:211], v[210:211], v[18:19]
	v_cvt_pk_bf16_f32 v7, v18, v19
	s_waitcnt lgkmcnt(1)
	v_mfma_f32_32x32x16_bf16 v[112:127], v[2:5], v[144:147], v[112:127]
	ds_read_b128 v[14:17], v0 offset:160
	ds_read_b128 v[80:83], v0 offset:6816
	v_pk_add_f32 v[210:211], v[210:211], v[20:21]
	v_pk_add_f32 v[210:211], v[210:211], v[22:23]
	v_cvt_pk_bf16_f32 v8, v20, v21
	v_cvt_pk_bf16_f32 v9, v22, v23
	s_waitcnt lgkmcnt(2)
	v_mfma_f32_32x32x16_bf16 v[96:111], v[206:209], v[144:147], v[96:111]
	v_pk_add_f32 v[210:211], v[210:211], v[24:25]
	v_cvt_pk_bf16_f32 v2, v24, v25
	s_waitcnt lgkmcnt(1)
	v_mfma_f32_32x32x16_bf16 v[112:127], v[14:17], v[148:151], v[112:127]
	v_pk_add_f32 v[210:211], v[210:211], v[26:27]
	v_cvt_pk_bf16_f32 v3, v26, v27
	s_waitcnt lgkmcnt(0)
	v_mfma_f32_32x32x16_bf16 v[96:111], v[80:83], v[148:151], v[96:111]
	v_pk_add_f32 v[210:211], v[210:211], v[28:29]
	v_pk_add_f32 v[210:211], v[210:211], v[30:31]
	v_add_f32_e32 v0, v210, v211
	v_cvt_pk_bf16_f32 v4, v28, v29
	v_cvt_pk_bf16_f32 v5, v30, v31
	s_mul_i32 s4, s71, 0x2400
	v_add_u32_e32 v206, s4, v200
	ds_read_b128 v[16:19], v206 offset:53248
	ds_read_b128 v[202:205], v206 offset:57856
	s_cmp_ge_i32 s67, s65
	v_add_f32_e32 v201, v201, v0
	s_cbranch_scc1 .LBB0_682
	s_sub_i32 s2, s68, 64
	s_cmp_le_i32 s2, s63
	s_cbranch_scc1 .LBB0_680
	v_add_u32_e32 v0, s68, v197
	v_add_u32_e32 v15, 0xffffffa1, v0
	v_add_u32_e32 v14, 0xffffff81, v0
	v_cmp_le_i32_e64 s[2:3], v15, v184
	v_cmp_le_i32_e32 vcc, v14, v184
	s_nop 0
	v_cndmask_b32_e64 v96, v194, v96, s[2:3]
	v_cmp_lt_i32_e64 s[2:3], v14, v184
	v_add_u32_e32 v14, 0xffffffa2, v0
	v_cmp_le_i32_e64 s[4:5], v14, v184
	v_add_u32_e32 v14, 0xffffff83, v0
	s_nop 0
	v_cndmask_b32_e64 v97, v194, v97, s[4:5]
	v_cmp_le_i32_e64 s[4:5], v14, v184
	v_add_u32_e32 v14, 0xffffffa3, v0
	v_cmp_le_i32_e64 s[6:7], v14, v184
	v_add_u32_e32 v14, 0xffffff84, v0
	s_nop 0
	v_cndmask_b32_e64 v98, v194, v98, s[6:7]
	v_cmp_le_i32_e64 s[6:7], v14, v184
	v_add_u32_e32 v14, 0xffffffa4, v0
	v_cmp_le_i32_e64 s[8:9], v14, v184
	v_add_u32_e32 v14, 0xffffff89, v0
	s_nop 0
	v_cndmask_b32_e64 v99, v194, v99, s[8:9]
	v_cmp_le_i32_e64 s[8:9], v14, v184
	v_add_u32_e32 v14, 0xffffffa9, v0
	v_cmp_le_i32_e64 s[10:11], v14, v184
	v_add_u32_e32 v14, 0xffffff8a, v0
	s_nop 0
	v_cndmask_b32_e64 v100, v194, v100, s[10:11]
	v_cmp_le_i32_e64 s[10:11], v14, v184
	v_add_u32_e32 v14, 0xffffffaa, v0
	v_cmp_le_i32_e64 s[12:13], v14, v184
	v_add_u32_e32 v14, 0xffffff8b, v0
	s_nop 0
	v_cndmask_b32_e64 v101, v194, v101, s[12:13]
	v_cmp_le_i32_e64 s[12:13], v14, v184
	v_add_u32_e32 v14, 0xffffffab, v0
	v_cmp_le_i32_e64 s[14:15], v14, v184
	v_add_u32_e32 v14, 0xffffff8c, v0
	s_nop 0
	v_cndmask_b32_e64 v102, v194, v102, s[14:15]
	v_cmp_le_i32_e64 s[14:15], v14, v184
	v_add_u32_e32 v14, 0xffffffac, v0
	v_cmp_le_i32_e64 s[16:17], v14, v184
	v_add_u32_e32 v14, 0xffffff91, v0
	s_nop 0
	v_cndmask_b32_e64 v103, v194, v103, s[16:17]
	v_cmp_le_i32_e64 s[16:17], v14, v184
	v_add_u32_e32 v14, 0xffffffb1, v0
	v_cmp_le_i32_e64 s[18:19], v14, v184
	v_add_u32_e32 v14, 0xffffff92, v0
	s_nop 0
	v_cndmask_b32_e64 v104, v194, v104, s[18:19]
	v_cmp_le_i32_e64 s[18:19], v14, v184
	v_add_u32_e32 v14, 0xffffffb2, v0
	v_cmp_le_i32_e64 s[20:21], v14, v184
	v_add_u32_e32 v14, 0xffffff93, v0
	s_nop 0
	v_cndmask_b32_e64 v105, v194, v105, s[20:21]
	v_cmp_le_i32_e64 s[20:21], v14, v184
	v_add_u32_e32 v14, 0xffffffb3, v0
	v_cmp_le_i32_e64 s[22:23], v14, v184
	v_add_u32_e32 v14, 0xffffff94, v0
	s_nop 0
	v_cndmask_b32_e64 v106, v194, v106, s[22:23]
	v_cmp_le_i32_e64 s[22:23], v14, v184
	v_add_u32_e32 v14, 0xffffffb4, v0
	v_cmp_le_i32_e64 s[24:25], v14, v184
	v_add_u32_e32 v14, 0xffffff99, v0
	s_nop 0
	v_cndmask_b32_e64 v107, v194, v107, s[24:25]
	v_cmp_le_i32_e64 s[24:25], v14, v184
	v_add_u32_e32 v14, 0xffffffb9, v0
	v_cmp_le_i32_e64 s[26:27], v14, v184
	v_add_u32_e32 v14, 0xffffff9a, v0
	s_nop 0
	v_cndmask_b32_e64 v108, v194, v108, s[26:27]
	v_cmp_le_i32_e64 s[26:27], v14, v184
	v_add_u32_e32 v14, 0xffffffba, v0
	v_cmp_le_i32_e64 s[28:29], v14, v184
	v_add_u32_e32 v14, 0xffffff9b, v0
	s_nop 0
	v_cndmask_b32_e64 v109, v194, v109, s[28:29]
	v_cmp_le_i32_e64 s[28:29], v14, v184
	v_add_u32_e32 v14, 0xffffffbb, v0
	v_cmp_le_i32_e64 s[30:31], v14, v184
	v_add_u32_e32 v14, 0xffffff9c, v0
	v_add_u32_e32 v0, 0xffffffbc, v0
	v_cndmask_b32_e64 v110, v194, v110, s[30:31]
	v_cmp_le_i32_e64 s[30:31], v14, v184
	v_cmp_gt_i32_e64 s[34:35], v0, v184
	s_and_saveexec_b64 s[48:49], s[34:35]
	v_mov_b32_e32 v111, s59
	s_or_b64 exec, exec, s[48:49]
	v_cndmask_b32_e64 v113, v194, v113, s[2:3]
	v_cndmask_b32_e32 v112, v194, v112, vcc
	v_cndmask_b32_e64 v114, v194, v114, s[4:5]
	v_cndmask_b32_e64 v115, v194, v115, s[6:7]
	v_cndmask_b32_e64 v116, v194, v116, s[8:9]
	v_cndmask_b32_e64 v117, v194, v117, s[10:11]
	v_cndmask_b32_e64 v118, v194, v118, s[12:13]
	v_cndmask_b32_e64 v119, v194, v119, s[14:15]
	v_cndmask_b32_e64 v120, v194, v120, s[16:17]
	v_cndmask_b32_e64 v121, v194, v121, s[18:19]
	v_cndmask_b32_e64 v122, v194, v122, s[20:21]
	v_cndmask_b32_e64 v123, v194, v123, s[22:23]
	v_cndmask_b32_e64 v124, v194, v124, s[24:25]
	v_cndmask_b32_e64 v125, v194, v125, s[26:27]
	v_cndmask_b32_e64 v126, v194, v126, s[28:29]
	v_cndmask_b32_e64 v127, v194, v127, s[30:31]

.LBB0_685:
	s_mulk_i32 s71, 0x3400
	s_add_i32 s3, s71, 0
	s_xor_b32 s2, s69, 2
	v_add_u32_e32 v0, s3, v192
	s_mulk_i32 s2, 0x2400
	s_waitcnt vmcnt(5)
	ds_write_b128 v0, v[168:171]
	v_add_u32_e32 v0, s3, v185
	s_waitcnt vmcnt(4)
	ds_write_b128 v0, v[164:167] offset:128
	v_add_u32_e32 v0, s2, v193
	s_add_i32 s2, s67, 6
	s_min_i32 s2, s2, s66
	s_mov_b32 s3, s47
	v_add_u32_e32 v0, 0xd000, v0
	s_lshl_b64 s[4:5], s[2:3], 16
	s_lshl_b64 s[2:3], s[2:3], 12
	s_waitcnt vmcnt(3)
	ds_write2_b64 v0, v[160:161], v[162:163] offset1:2
	v_lshl_add_u64 v[2:3], v[186:187], 0, s[4:5]
	v_lshl_add_u64 v[4:5], v[188:189], 0, s[2:3]
	s_lshl_b64 s[2:3], s[46:47], 7
	global_load_dwordx4 v[168:171], v[2:3], off
	global_load_dwordx4 v[164:167], v[4:5], off
	v_lshl_add_u64 v[2:3], v[190:191], 0, s[2:3]
	global_load_dwordx4 v[160:163], v[2:3], off
	s_add_i32 s46, s67, 2
	s_cmp_ge_i32 s67, s65
	s_cbranch_scc1 .LBB0_696
	s_and_b32 s2, s46, 2
	s_mulk_i32 s2, 0x3400
	v_add_u32_e32 v0, s2, v196
	ds_read_b128 v[2:5], v0
	ds_read_b128 v[6:9], v0 offset:6656
	s_waitcnt lgkmcnt(1)
	v_mfma_f32_32x32x16_bf16 v[112:127], v[2:5], v[128:131], v[48:63]
	ds_read_b128 v[10:13], v0 offset:32
	ds_read_b128 v[202:205], v0 offset:6688
	v_cvt_pk_bf16_f32 v176, v80, v81
	s_waitcnt lgkmcnt(2)
	v_mfma_f32_32x32x16_bf16 v[96:111], v[6:9], v[128:131], v[48:63]
	v_pk_add_f32 v[210:211], v[80:81], v[82:83]
	v_cvt_pk_bf16_f32 v177, v82, v83
	s_waitcnt lgkmcnt(1)
	v_mfma_f32_32x32x16_bf16 v[112:127], v[10:13], v[132:135], v[112:127]
	ds_read_b128 v[2:5], v0 offset:64
	ds_read_b128 v[6:9], v0 offset:6720
	v_pk_add_f32 v[210:211], v[210:211], v[84:85]
	v_pk_add_f32 v[210:211], v[210:211], v[86:87]
	v_cvt_pk_bf16_f32 v178, v84, v85
	v_cvt_pk_bf16_f32 v179, v86, v87
	s_waitcnt lgkmcnt(2)
	v_mfma_f32_32x32x16_bf16 v[96:111], v[202:205], v[132:135], v[96:111]
	v_pk_add_f32 v[210:211], v[210:211], v[88:89]
	v_cvt_pk_bf16_f32 v10, v88, v89
	s_waitcnt lgkmcnt(1)
	v_mfma_f32_32x32x16_bf16 v[112:127], v[2:5], v[136:139], v[112:127]
	ds_read_b128 v[80:83], v0 offset:96
	ds_read_b128 v[202:205], v0 offset:6752
	v_pk_add_f32 v[210:211], v[210:211], v[90:91]
	v_cvt_pk_bf16_f32 v11, v90, v91
	s_waitcnt lgkmcnt(2)
	v_mfma_f32_32x32x16_bf16 v[96:111], v[6:9], v[136:139], v[96:111]
	v_pk_add_f32 v[210:211], v[210:211], v[92:93]
	v_pk_add_f32 v[210:211], v[210:211], v[94:95]
	v_cvt_pk_bf16_f32 v12, v92, v93
	v_cvt_pk_bf16_f32 v13, v94, v95
	s_waitcnt lgkmcnt(1)
	v_mfma_f32_32x32x16_bf16 v[112:127], v[80:83], v[140:143], v[112:127]
	ds_read_b128 v[2:5], v0 offset:128
	ds_read_b128 v[206:209], v0 offset:6784
	v_pk_add_f32 v[210:211], v[210:211], v[16:17]
	v_cvt_pk_bf16_f32 v6, v16, v17
	s_waitcnt lgkmcnt(2)
	v_mfma_f32_32x32x16_bf16 v[96:111], v[202:205], v[140:143], v[96:111]
	v_pk_add_f32 v[210:211], v[210:211], v[18:19]
	v_cvt_pk_bf16_f32 v7, v18, v19
	s_waitcnt lgkmcnt(1)
	v_mfma_f32_32x32x16_bf16 v[112:127], v[2:5], v[144:147], v[112:127]
	ds_read_b128 v[14:17], v0 offset:160
	ds_read_b128 v[80:83], v0 offset:6816
	v_pk_add_f32 v[210:211], v[210:211], v[20:21]
	v_pk_add_f32 v[210:211], v[210:211], v[22:23]
	v_cvt_pk_bf16_f32 v8, v20, v21
	v_cvt_pk_bf16_f32 v9, v22, v23
	s_waitcnt lgkmcnt(2)
	v_mfma_f32_32x32x16_bf16 v[96:111], v[206:209], v[144:147], v[96:111]
	v_pk_add_f32 v[210:211], v[210:211], v[24:25]
	v_cvt_pk_bf16_f32 v2, v24, v25
	s_waitcnt lgkmcnt(1)
	v_mfma_f32_32x32x16_bf16 v[112:127], v[14:17], v[148:151], v[112:127]
	v_pk_add_f32 v[210:211], v[210:211], v[26:27]
	v_cvt_pk_bf16_f32 v3, v26, v27
	s_waitcnt lgkmcnt(0)
	v_mfma_f32_32x32x16_bf16 v[96:111], v[80:83], v[148:151], v[96:111]
	v_pk_add_f32 v[210:211], v[210:211], v[28:29]
	v_pk_add_f32 v[210:211], v[210:211], v[30:31]
	v_add_f32_e32 v0, v210, v211
	v_cvt_pk_bf16_f32 v4, v28, v29
	v_cvt_pk_bf16_f32 v5, v30, v31
	s_mul_i32 s4, s69, 0x2400
	v_add_u32_e32 v206, s4, v200
	ds_read_b128 v[16:19], v206 offset:53248
	ds_read_b128 v[202:205], v206 offset:57856
	s_cmp_ge_i32 s70, s65
	v_add_f32_e32 v201, v201, v0
	s_cbranch_scc1 .LBB0_693
	s_cmp_le_i32 s68, s63
	s_cbranch_scc1 .LBB0_691
	v_add_u32_e32 v0, s68, v197
	v_subrev_u32_e32 v15, 31, v0
	v_subrev_u32_e32 v14, 63, v0
	v_cmp_le_i32_e64 s[2:3], v15, v184
	v_cmp_le_i32_e32 vcc, v14, v184
	s_nop 0
	v_cndmask_b32_e64 v96, v194, v96, s[2:3]
	v_cmp_lt_i32_e64 s[2:3], v14, v184
	v_subrev_u32_e32 v14, 30, v0
	v_cmp_le_i32_e64 s[4:5], v14, v184
	v_subrev_u32_e32 v14, 61, v0
	s_nop 0
	v_cndmask_b32_e64 v97, v194, v97, s[4:5]
	v_cmp_le_i32_e64 s[4:5], v14, v184
	v_subrev_u32_e32 v14, 29, v0
	v_cmp_le_i32_e64 s[6:7], v14, v184
	v_subrev_u32_e32 v14, 60, v0
	s_nop 0
	v_cndmask_b32_e64 v98, v194, v98, s[6:7]
	v_cmp_le_i32_e64 s[6:7], v14, v184
	v_subrev_u32_e32 v14, 28, v0
	v_cmp_le_i32_e64 s[8:9], v14, v184
	v_subrev_u32_e32 v14, 55, v0
	s_nop 0
	v_cndmask_b32_e64 v99, v194, v99, s[8:9]
	v_cmp_le_i32_e64 s[8:9], v14, v184
	v_subrev_u32_e32 v14, 23, v0
	v_cmp_le_i32_e64 s[10:11], v14, v184
	v_subrev_u32_e32 v14, 54, v0
	s_nop 0
	v_cndmask_b32_e64 v100, v194, v100, s[10:11]
	v_cmp_le_i32_e64 s[10:11], v14, v184
	v_subrev_u32_e32 v14, 22, v0
	v_cmp_le_i32_e64 s[12:13], v14, v184
	v_subrev_u32_e32 v14, 53, v0
	s_nop 0
	v_cndmask_b32_e64 v101, v194, v101, s[12:13]
	v_cmp_le_i32_e64 s[12:13], v14, v184
	v_subrev_u32_e32 v14, 21, v0
	v_cmp_le_i32_e64 s[14:15], v14, v184
	v_subrev_u32_e32 v14, 52, v0
	s_nop 0
	v_cndmask_b32_e64 v102, v194, v102, s[14:15]
	v_cmp_le_i32_e64 s[14:15], v14, v184
	v_subrev_u32_e32 v14, 20, v0
	v_cmp_le_i32_e64 s[16:17], v14, v184
	v_subrev_u32_e32 v14, 47, v0
	s_nop 0
	v_cndmask_b32_e64 v103, v194, v103, s[16:17]
	v_cmp_le_i32_e64 s[16:17], v14, v184
	v_add_u32_e32 v14, -15, v0
	v_cmp_le_i32_e64 s[18:19], v14, v184
	v_subrev_u32_e32 v14, 46, v0
	s_nop 0
	v_cndmask_b32_e64 v104, v194, v104, s[18:19]
	v_cmp_le_i32_e64 s[18:19], v14, v184
	v_add_u32_e32 v14, -14, v0
	v_cmp_le_i32_e64 s[20:21], v14, v184
	v_subrev_u32_e32 v14, 45, v0
	s_nop 0
	v_cndmask_b32_e64 v105, v194, v105, s[20:21]
	v_cmp_le_i32_e64 s[20:21], v14, v184
	v_add_u32_e32 v14, -13, v0
	v_cmp_le_i32_e64 s[22:23], v14, v184
	v_subrev_u32_e32 v14, 44, v0
	s_nop 0
	v_cndmask_b32_e64 v106, v194, v106, s[22:23]
	v_cmp_le_i32_e64 s[22:23], v14, v184
	v_add_u32_e32 v14, -12, v0
	v_cmp_le_i32_e64 s[24:25], v14, v184
	v_subrev_u32_e32 v14, 39, v0
	s_nop 0
	v_cndmask_b32_e64 v107, v194, v107, s[24:25]
	v_cmp_le_i32_e64 s[24:25], v14, v184
	v_add_u32_e32 v14, -7, v0
	v_cmp_le_i32_e64 s[26:27], v14, v184
	v_subrev_u32_e32 v14, 38, v0
	s_nop 0
	v_cndmask_b32_e64 v108, v194, v108, s[26:27]
	v_cmp_le_i32_e64 s[26:27], v14, v184
	v_add_u32_e32 v14, -6, v0
	v_cmp_le_i32_e64 s[28:29], v14, v184
	v_subrev_u32_e32 v14, 37, v0
	s_nop 0
	v_cndmask_b32_e64 v109, v194, v109, s[28:29]
	v_cmp_le_i32_e64 s[28:29], v14, v184
	v_add_u32_e32 v14, -5, v0
	v_cmp_le_i32_e64 s[30:31], v14, v184
	v_subrev_u32_e32 v14, 36, v0
	v_add_u32_e32 v0, -4, v0
	v_cndmask_b32_e64 v110, v194, v110, s[30:31]
	v_cmp_le_i32_e64 s[30:31], v14, v184
	v_cmp_gt_i32_e64 s[34:35], v0, v184
	s_and_saveexec_b64 s[48:49], s[34:35]
	v_mov_b32_e32 v111, s59
	s_or_b64 exec, exec, s[48:49]
	v_cndmask_b32_e64 v113, v194, v113, s[2:3]
	v_cndmask_b32_e32 v112, v194, v112, vcc
	v_cndmask_b32_e64 v114, v194, v114, s[4:5]
	v_cndmask_b32_e64 v115, v194, v115, s[6:7]
	v_cndmask_b32_e64 v116, v194, v116, s[8:9]
	v_cndmask_b32_e64 v117, v194, v117, s[10:11]
	v_cndmask_b32_e64 v118, v194, v118, s[12:13]
	v_cndmask_b32_e64 v119, v194, v119, s[14:15]
	v_cndmask_b32_e64 v120, v194, v120, s[16:17]
	v_cndmask_b32_e64 v121, v194, v121, s[18:19]
	v_cndmask_b32_e64 v122, v194, v122, s[20:21]
	v_cndmask_b32_e64 v123, v194, v123, s[22:23]
	v_cndmask_b32_e64 v124, v194, v124, s[24:25]
	v_cndmask_b32_e64 v125, v194, v125, s[26:27]
	v_cndmask_b32_e64 v126, v194, v126, s[28:29]
	v_cndmask_b32_e64 v127, v194, v127, s[30:31]
